# best4 + nt on norm_unit Q/K loads
# baseline (speedup 1.0000x reference)
; __device__ __forceinline__ float bf_lo(unsigned w) { return __uint_as_float(w << 16); }
; __device__ __forceinline__ float bf_hi(unsigned w) { return __uint_as_float(w & 0xffff0000u); }
; __device__ __forceinline__ void norm_unit(const Ctx& c, int l, int tile) {
;     ...
;     for (int a = 0; a < 2; ++a)
; #pragma unroll
;         for (int hh = 0; hh < 2; ++hh) { const u32x4* p = (const u32x4*)((a == 0 ? Q : K) + (size_t)tok * 512 + (2 * part + hh) * 64);
;             float s0 = 0.f, s1 = 0.f;
; #pragma unroll
;             for (int j = 0; j < 8; ++j) { const u32x4 w = p[j];
;                 s0 += bf_lo(w.x) * bf_lo(w.x) + bf_hi(w.x) * bf_hi(w.x) + bf_lo(w.y) * bf_lo(w.y) + bf_hi(w.y) * bf_hi(w.y);
;                 s1 += bf_lo(w.z) * bf_lo(w.z) + bf_hi(w.z) * bf_hi(w.z) + bf_lo(w.w) * bf_lo(w.w) + bf_hi(w.w) * bf_hi(w.w); }
;             res[a * 2 + hh] = (s0 + s1) * 1.0001f + 1e-30f; }
.LBB0_314:
	v_readlane_b32 s12, v253, 0
	v_readlane_b32 s13, v253, 1
	s_load_dwordx4 s[20:23], s[12:13], 0xa8
	v_ashrrev_i32_e32 v17, 31, v16
	s_waitcnt lgkmcnt(0)
	v_lshlrev_b64 v[0:1], 10, v[16:17]
	s_mov_b64 s[12:13], 0x4000000
	s_mov_b64 s[42:43], 0x6000000
	s_waitcnt lgkmcnt(0)
	v_lshl_add_u64 v[12:13], s[22:23], 0, v[0:1]
	v_lshl_add_u64 v[14:15], v[12:13], 0, s[12:13]
	v_lshl_add_u64 v[20:21], v[14:15], 0, v[96:97]
	global_load_dwordx4 v[0:3], v[20:21], off offset:48 nt
	global_load_dwordx4 v[4:7], v[20:21], off offset:32 nt
	global_load_dwordx4 v[8:11], v[20:21], off offset:16 nt
	global_load_dwordx4 v[28:31], v[20:21], off nt
	v_lshl_add_u64 v[12:13], v[12:13], 0, s[42:43]
	s_waitcnt vmcnt(0)
	v_and_b32_e32 v19, 0xffff0000, v28
	v_lshlrev_b32_e32 v17, 16, v28
	v_mul_f32_e32 v19, v19, v19
	v_fmac_f32_e32 v19, v17, v17
	v_lshlrev_b32_e32 v17, 16, v29
	v_fmac_f32_e32 v19, v17, v17
	v_and_b32_e32 v17, 0xffff0000, v29
	v_and_b32_e32 v28, 0xffff0000, v30
	v_fmac_f32_e32 v19, v17, v17
	v_lshlrev_b32_e32 v17, 16, v30
	v_mul_f32_e32 v28, v28, v28
	v_fmac_f32_e32 v28, v17, v17
	v_lshlrev_b32_e32 v17, 16, v31
	v_fmac_f32_e32 v28, v17, v17
	v_and_b32_e32 v17, 0xffff0000, v31
	v_fmac_f32_e32 v28, v17, v17
	v_lshlrev_b32_e32 v17, 16, v8
	v_and_b32_e32 v8, 0xffff0000, v8
	v_mul_f32_e32 v8, v8, v8
	v_fmac_f32_e32 v8, v17, v17
	v_lshlrev_b32_e32 v17, 16, v9
	v_fmac_f32_e32 v8, v17, v17
	v_and_b32_e32 v9, 0xffff0000, v9
	v_fmac_f32_e32 v8, v9, v9
	v_lshlrev_b32_e32 v9, 16, v10
	v_and_b32_e32 v10, 0xffff0000, v10
	v_mul_f32_e32 v10, v10, v10
	v_fmac_f32_e32 v10, v9, v9
	v_lshlrev_b32_e32 v9, 16, v11
	v_fmac_f32_e32 v10, v9, v9
	v_and_b32_e32 v9, 0xffff0000, v11
	v_fmac_f32_e32 v10, v9, v9
	v_add_f32_e32 v9, v28, v10
	v_lshlrev_b32_e32 v10, 16, v4
	v_and_b32_e32 v4, 0xffff0000, v4
	v_mul_f32_e32 v4, v4, v4
	v_fmac_f32_e32 v4, v10, v10
	v_lshlrev_b32_e32 v10, 16, v5
	v_fmac_f32_e32 v4, v10, v10
	v_and_b32_e32 v5, 0xffff0000, v5
	v_fmac_f32_e32 v4, v5, v5
	v_lshlrev_b32_e32 v5, 16, v6
	v_and_b32_e32 v6, 0xffff0000, v6
	v_mul_f32_e32 v6, v6, v6
	v_fmac_f32_e32 v6, v5, v5
	v_lshlrev_b32_e32 v5, 16, v7
	v_fmac_f32_e32 v6, v5, v5
	v_and_b32_e32 v5, 0xffff0000, v7
	v_fmac_f32_e32 v6, v5, v5
	v_add_f32_e32 v5, v9, v6
	v_lshlrev_b32_e32 v6, 16, v0
	v_and_b32_e32 v0, 0xffff0000, v0
	v_mul_f32_e32 v0, v0, v0
	v_fmac_f32_e32 v0, v6, v6
	v_lshlrev_b32_e32 v6, 16, v1
	v_add_f32_e32 v8, v19, v8
	v_fmac_f32_e32 v0, v6, v6
	v_and_b32_e32 v1, 0xffff0000, v1
	v_add_f32_e32 v4, v8, v4
	v_fmac_f32_e32 v0, v1, v1
	v_and_b32_e32 v1, 0xffff0000, v2
	v_add_f32_e32 v17, v4, v0
	v_lshlrev_b32_e32 v0, 16, v2
	v_mul_f32_e32 v1, v1, v1
	v_fmac_f32_e32 v1, v0, v0
	v_lshlrev_b32_e32 v0, 16, v3
	v_fmac_f32_e32 v1, v0, v0
	v_and_b32_e32 v0, 0xffff0000, v3
	v_fmac_f32_e32 v1, v0, v0
	v_add_f32_e32 v19, v5, v1
	global_load_dwordx4 v[0:3], v[20:21], off offset:112 nt
	global_load_dwordx4 v[4:7], v[20:21], off offset:96 nt
	global_load_dwordx4 v[8:11], v[20:21], off offset:80 nt
	global_load_dwordx4 v[28:31], v[20:21], off offset:64 nt
	s_waitcnt vmcnt(0)
	v_and_b32_e32 v21, 0xffff0000, v28
	v_lshlrev_b32_e32 v20, 16, v28
	v_mul_f32_e32 v21, v21, v21
	v_fmac_f32_e32 v21, v20, v20
	v_lshlrev_b32_e32 v20, 16, v29
	v_fmac_f32_e32 v21, v20, v20
	v_and_b32_e32 v20, 0xffff0000, v29
	v_fmac_f32_e32 v21, v20, v20
	v_add_f32_e32 v17, v17, v21
	v_and_b32_e32 v21, 0xffff0000, v30
	v_lshlrev_b32_e32 v20, 16, v30
	v_mul_f32_e32 v21, v21, v21
	v_fmac_f32_e32 v21, v20, v20
	v_lshlrev_b32_e32 v20, 16, v31
	v_fmac_f32_e32 v21, v20, v20
	v_and_b32_e32 v20, 0xffff0000, v31
	v_fmac_f32_e32 v21, v20, v20
	v_lshlrev_b32_e32 v20, 16, v8
	v_and_b32_e32 v8, 0xffff0000, v8
	v_mul_f32_e32 v8, v8, v8
	v_fmac_f32_e32 v8, v20, v20
	v_lshlrev_b32_e32 v20, 16, v9
	v_fmac_f32_e32 v8, v20, v20
	v_and_b32_e32 v9, 0xffff0000, v9
	v_fmac_f32_e32 v8, v9, v9
	v_lshlrev_b32_e32 v9, 16, v10
	v_and_b32_e32 v10, 0xffff0000, v10
	v_mul_f32_e32 v10, v10, v10
	v_fmac_f32_e32 v10, v9, v9
	v_lshlrev_b32_e32 v9, 16, v11
	v_fmac_f32_e32 v10, v9, v9
	v_and_b32_e32 v9, 0xffff0000, v11
	v_add_f32_e32 v19, v19, v21
	v_fmac_f32_e32 v10, v9, v9
	v_add_f32_e32 v9, v19, v10
	v_lshlrev_b32_e32 v10, 16, v4
	v_and_b32_e32 v4, 0xffff0000, v4
	v_mul_f32_e32 v4, v4, v4
	v_fmac_f32_e32 v4, v10, v10
	v_lshlrev_b32_e32 v10, 16, v5
	v_fmac_f32_e32 v4, v10, v10
	v_and_b32_e32 v5, 0xffff0000, v5
	v_fmac_f32_e32 v4, v5, v5
	v_lshlrev_b32_e32 v5, 16, v6
	v_and_b32_e32 v6, 0xffff0000, v6
	v_mul_f32_e32 v6, v6, v6
	v_fmac_f32_e32 v6, v5, v5
	v_lshlrev_b32_e32 v5, 16, v7
	v_fmac_f32_e32 v6, v5, v5
	v_and_b32_e32 v5, 0xffff0000, v7
	v_fmac_f32_e32 v6, v5, v5
	v_add_f32_e32 v5, v9, v6
	v_lshlrev_b32_e32 v6, 16, v0
	v_and_b32_e32 v0, 0xffff0000, v0
	v_mul_f32_e32 v0, v0, v0
	v_fmac_f32_e32 v0, v6, v6
	v_lshlrev_b32_e32 v6, 16, v1
	v_fmac_f32_e32 v0, v6, v6
	v_and_b32_e32 v1, 0xffff0000, v1
	v_fmac_f32_e32 v0, v1, v1
	v_lshlrev_b32_e32 v1, 16, v2
	v_and_b32_e32 v2, 0xffff0000, v2
	v_mul_f32_e32 v2, v2, v2
	v_fmac_f32_e32 v2, v1, v1
	v_lshlrev_b32_e32 v1, 16, v3
	v_add_f32_e32 v8, v17, v8
	v_fmac_f32_e32 v2, v1, v1
	v_and_b32_e32 v1, 0xffff0000, v3
	v_add_f32_e32 v4, v8, v4
	v_fmac_f32_e32 v2, v1, v1
	v_add_f32_e32 v0, v4, v0
	v_add_f32_e32 v1, v5, v2
	v_mov_b32_e32 v19, v97
	v_add_f32_e32 v0, v0, v1
	v_lshl_add_u64 v[14:15], v[14:15], 0, v[18:19]
	v_fmamk_f32 v17, v0, 0x3f800347, v217
	global_load_dwordx4 v[0:3], v[14:15], off offset:48 nt
	global_load_dwordx4 v[4:7], v[14:15], off offset:32 nt
	global_load_dwordx4 v[8:11], v[14:15], off offset:16 nt
	global_load_dwordx4 v[28:31], v[14:15], off nt
	s_waitcnt vmcnt(0)
; __device__ __forceinline__ float bf_lo(unsigned w) { return __uint_as_float(w << 16); }
; __device__ __forceinline__ float bf_hi(unsigned w) { return __uint_as_float(w & 0xffff0000u); }
; __device__ __forceinline__ void norm_unit(const Ctx& c, int l, int tile) {
;     ...
;     for (int a = 0; a < 2; ++a)
; #pragma unroll
;         for (int hh = 0; hh < 2; ++hh) { const u32x4* p = (const u32x4*)((a == 0 ? Q : K) + (size_t)tok * 512 + (2 * part + hh) * 64);
;             float s0 = 0.f, s1 = 0.f;
; #pragma unroll
;             for (int j = 0; j < 8; ++j) { const u32x4 w = p[j];
;                 s0 += bf_lo(w.x) * bf_lo(w.x) + bf_hi(w.x) * bf_hi(w.x) + bf_lo(w.y) * bf_lo(w.y) + bf_hi(w.y) * bf_hi(w.y);
;                 s1 += bf_lo(w.z) * bf_lo(w.z) + bf_hi(w.z) * bf_hi(w.z) + bf_lo(w.w) * bf_lo(w.w) + bf_hi(w.w) * bf_hi(w.w); }
;             res[a * 2 + hh] = (s0 + s1) * 1.0001f + 1e-30f; }
	v_and_b32_e32 v21, 0xffff0000, v28
	v_lshlrev_b32_e32 v20, 16, v28
	v_mul_f32_e32 v21, v21, v21
	v_fmac_f32_e32 v21, v20, v20
	v_lshlrev_b32_e32 v20, 16, v29
	v_fmac_f32_e32 v21, v20, v20
	v_and_b32_e32 v20, 0xffff0000, v29
	v_and_b32_e32 v28, 0xffff0000, v30
	v_fmac_f32_e32 v21, v20, v20
	v_lshlrev_b32_e32 v20, 16, v30
	v_mul_f32_e32 v28, v28, v28
	v_fmac_f32_e32 v28, v20, v20
	v_lshlrev_b32_e32 v20, 16, v31
	v_fmac_f32_e32 v28, v20, v20
	v_and_b32_e32 v20, 0xffff0000, v31
	v_fmac_f32_e32 v28, v20, v20
	v_lshlrev_b32_e32 v20, 16, v8
	v_and_b32_e32 v8, 0xffff0000, v8
	v_mul_f32_e32 v8, v8, v8
	v_fmac_f32_e32 v8, v20, v20
	v_lshlrev_b32_e32 v20, 16, v9
	v_fmac_f32_e32 v8, v20, v20
	v_and_b32_e32 v9, 0xffff0000, v9
	v_fmac_f32_e32 v8, v9, v9
	v_lshlrev_b32_e32 v9, 16, v10
	v_and_b32_e32 v10, 0xffff0000, v10
	v_mul_f32_e32 v10, v10, v10
	v_fmac_f32_e32 v10, v9, v9
	v_lshlrev_b32_e32 v9, 16, v11
	v_fmac_f32_e32 v10, v9, v9
	v_and_b32_e32 v9, 0xffff0000, v11
	v_fmac_f32_e32 v10, v9, v9
	v_add_f32_e32 v9, v28, v10
	v_lshlrev_b32_e32 v10, 16, v4
	v_and_b32_e32 v4, 0xffff0000, v4
	v_mul_f32_e32 v4, v4, v4
	v_fmac_f32_e32 v4, v10, v10
	v_lshlrev_b32_e32 v10, 16, v5
	v_fmac_f32_e32 v4, v10, v10
	v_and_b32_e32 v5, 0xffff0000, v5
	v_fmac_f32_e32 v4, v5, v5
	v_lshlrev_b32_e32 v5, 16, v6
	v_and_b32_e32 v6, 0xffff0000, v6
	v_mul_f32_e32 v6, v6, v6
	v_fmac_f32_e32 v6, v5, v5
	v_lshlrev_b32_e32 v5, 16, v7
	v_fmac_f32_e32 v6, v5, v5
	v_and_b32_e32 v5, 0xffff0000, v7
	v_fmac_f32_e32 v6, v5, v5
	v_add_f32_e32 v5, v9, v6
	v_lshlrev_b32_e32 v6, 16, v0
	v_and_b32_e32 v0, 0xffff0000, v0
	v_mul_f32_e32 v0, v0, v0
	v_fmac_f32_e32 v0, v6, v6
	v_lshlrev_b32_e32 v6, 16, v1
	v_add_f32_e32 v8, v21, v8
	v_fmac_f32_e32 v0, v6, v6
	v_and_b32_e32 v1, 0xffff0000, v1
	v_add_f32_e32 v4, v8, v4
	v_fmac_f32_e32 v0, v1, v1
	v_and_b32_e32 v1, 0xffff0000, v2
	v_add_f32_e32 v20, v4, v0
	v_lshlrev_b32_e32 v0, 16, v2
	v_mul_f32_e32 v1, v1, v1
	v_fmac_f32_e32 v1, v0, v0
	v_lshlrev_b32_e32 v0, 16, v3
	v_fmac_f32_e32 v1, v0, v0
	v_and_b32_e32 v0, 0xffff0000, v3
	v_fmac_f32_e32 v1, v0, v0
	v_add_f32_e32 v21, v5, v1
	global_load_dwordx4 v[0:3], v[14:15], off offset:112 nt
	global_load_dwordx4 v[4:7], v[14:15], off offset:96 nt
	global_load_dwordx4 v[8:11], v[14:15], off offset:80 nt
	global_load_dwordx4 v[28:31], v[14:15], off offset:64 nt
	s_waitcnt vmcnt(0)
	v_and_b32_e32 v15, 0xffff0000, v28
	v_lshlrev_b32_e32 v14, 16, v28
	v_mul_f32_e32 v15, v15, v15
	v_fmac_f32_e32 v15, v14, v14
	v_lshlrev_b32_e32 v14, 16, v29
	v_fmac_f32_e32 v15, v14, v14
	v_and_b32_e32 v14, 0xffff0000, v29
	v_fmac_f32_e32 v15, v14, v14
	v_add_f32_e32 v14, v20, v15
	v_and_b32_e32 v20, 0xffff0000, v30
	v_lshlrev_b32_e32 v15, 16, v30
	v_mul_f32_e32 v20, v20, v20
	v_fmac_f32_e32 v20, v15, v15
	v_lshlrev_b32_e32 v15, 16, v31
	v_fmac_f32_e32 v20, v15, v15
	v_and_b32_e32 v15, 0xffff0000, v31
	v_fmac_f32_e32 v20, v15, v15
	v_add_f32_e32 v15, v21, v20
	v_lshlrev_b32_e32 v20, 16, v8
	v_and_b32_e32 v8, 0xffff0000, v8
	v_mul_f32_e32 v8, v8, v8
	v_fmac_f32_e32 v8, v20, v20
	v_lshlrev_b32_e32 v20, 16, v9
	v_fmac_f32_e32 v8, v20, v20
	v_and_b32_e32 v9, 0xffff0000, v9
	v_fmac_f32_e32 v8, v9, v9
	v_lshlrev_b32_e32 v9, 16, v10
	v_and_b32_e32 v10, 0xffff0000, v10
	v_mul_f32_e32 v10, v10, v10
	v_fmac_f32_e32 v10, v9, v9
	v_lshlrev_b32_e32 v9, 16, v11
	v_fmac_f32_e32 v10, v9, v9
	v_and_b32_e32 v9, 0xffff0000, v11
	v_fmac_f32_e32 v10, v9, v9
	v_add_f32_e32 v9, v15, v10
	v_lshlrev_b32_e32 v10, 16, v4
	v_and_b32_e32 v4, 0xffff0000, v4
	v_mul_f32_e32 v4, v4, v4
	v_fmac_f32_e32 v4, v10, v10
	v_lshlrev_b32_e32 v10, 16, v5
	v_fmac_f32_e32 v4, v10, v10
	v_and_b32_e32 v5, 0xffff0000, v5
	v_fmac_f32_e32 v4, v5, v5
	v_lshlrev_b32_e32 v5, 16, v6
	v_and_b32_e32 v6, 0xffff0000, v6
	v_mul_f32_e32 v6, v6, v6
	v_fmac_f32_e32 v6, v5, v5
	v_lshlrev_b32_e32 v5, 16, v7
	v_fmac_f32_e32 v6, v5, v5
	v_and_b32_e32 v5, 0xffff0000, v7
	v_fmac_f32_e32 v6, v5, v5
	v_add_f32_e32 v5, v9, v6
	v_lshlrev_b32_e32 v6, 16, v0
	v_and_b32_e32 v0, 0xffff0000, v0
	v_mul_f32_e32 v0, v0, v0
	v_fmac_f32_e32 v0, v6, v6
	v_lshlrev_b32_e32 v6, 16, v1
	v_fmac_f32_e32 v0, v6, v6
	v_and_b32_e32 v1, 0xffff0000, v1
	v_fmac_f32_e32 v0, v1, v1
	v_lshlrev_b32_e32 v1, 16, v2
	v_and_b32_e32 v2, 0xffff0000, v2
	v_mul_f32_e32 v2, v2, v2
	v_fmac_f32_e32 v2, v1, v1
	v_lshlrev_b32_e32 v1, 16, v3
	v_add_f32_e32 v8, v14, v8
	v_fmac_f32_e32 v2, v1, v1
	v_and_b32_e32 v1, 0xffff0000, v3
	v_add_f32_e32 v4, v8, v4
	v_fmac_f32_e32 v2, v1, v1
	v_add_f32_e32 v0, v4, v0
	v_add_f32_e32 v1, v5, v2
	v_add_f32_e32 v0, v0, v1
	v_lshl_add_u64 v[14:15], v[12:13], 0, v[96:97]
	v_fmamk_f32 v20, v0, 0x3f800347, v217
	global_load_dwordx4 v[0:3], v[14:15], off offset:48 nt
	global_load_dwordx4 v[4:7], v[14:15], off offset:32 nt
	global_load_dwordx4 v[8:11], v[14:15], off offset:16 nt
	global_load_dwordx4 v[28:31], v[14:15], off nt
	v_lshl_add_u64 v[12:13], v[12:13], 0, v[18:19]
	s_waitcnt vmcnt(0)
; __device__ __forceinline__ float bf_lo(unsigned w) { return __uint_as_float(w << 16); }
; __device__ __forceinline__ float bf_hi(unsigned w) { return __uint_as_float(w & 0xffff0000u); }
; __device__ __forceinline__ void norm_unit(const Ctx& c, int l, int tile) {
;     ...
;     for (int a = 0; a < 2; ++a)
; #pragma unroll
;         for (int hh = 0; hh < 2; ++hh) { const u32x4* p = (const u32x4*)((a == 0 ? Q : K) + (size_t)tok * 512 + (2 * part + hh) * 64);
;             float s0 = 0.f, s1 = 0.f;
; #pragma unroll
;             for (int j = 0; j < 8; ++j) { const u32x4 w = p[j];
;                 s0 += bf_lo(w.x) * bf_lo(w.x) + bf_hi(w.x) * bf_hi(w.x) + bf_lo(w.y) * bf_lo(w.y) + bf_hi(w.y) * bf_hi(w.y);
;                 s1 += bf_lo(w.z) * bf_lo(w.z) + bf_hi(w.z) * bf_hi(w.z) + bf_lo(w.w) * bf_lo(w.w) + bf_hi(w.w) * bf_hi(w.w); }
;             res[a * 2 + hh] = (s0 + s1) * 1.0001f + 1e-30f; }
	v_lshlrev_b32_e32 v21, 16, v28
	v_and_b32_e32 v28, 0xffff0000, v28
	v_mul_f32_e32 v28, v28, v28
	v_fmac_f32_e32 v28, v21, v21
	v_lshlrev_b32_e32 v21, 16, v29
	v_fmac_f32_e32 v28, v21, v21
	v_and_b32_e32 v21, 0xffff0000, v29
	v_and_b32_e32 v29, 0xffff0000, v30
	v_fmac_f32_e32 v28, v21, v21
	v_lshlrev_b32_e32 v21, 16, v30
	v_mul_f32_e32 v29, v29, v29
	v_fmac_f32_e32 v29, v21, v21
	v_lshlrev_b32_e32 v21, 16, v31
	v_fmac_f32_e32 v29, v21, v21
	v_and_b32_e32 v21, 0xffff0000, v31
	v_fmac_f32_e32 v29, v21, v21
	v_lshlrev_b32_e32 v21, 16, v8
	v_and_b32_e32 v8, 0xffff0000, v8
	v_mul_f32_e32 v8, v8, v8
	v_fmac_f32_e32 v8, v21, v21
	v_lshlrev_b32_e32 v21, 16, v9
	v_fmac_f32_e32 v8, v21, v21
	v_and_b32_e32 v9, 0xffff0000, v9
	v_fmac_f32_e32 v8, v9, v9
	v_lshlrev_b32_e32 v9, 16, v10
	v_and_b32_e32 v10, 0xffff0000, v10
	v_mul_f32_e32 v10, v10, v10
	v_fmac_f32_e32 v10, v9, v9
	v_lshlrev_b32_e32 v9, 16, v11
	v_fmac_f32_e32 v10, v9, v9
	v_and_b32_e32 v9, 0xffff0000, v11
	v_fmac_f32_e32 v10, v9, v9
	v_add_f32_e32 v9, v29, v10
	v_lshlrev_b32_e32 v10, 16, v4
	v_and_b32_e32 v4, 0xffff0000, v4
	v_mul_f32_e32 v4, v4, v4
	v_fmac_f32_e32 v4, v10, v10
	v_lshlrev_b32_e32 v10, 16, v5
	v_fmac_f32_e32 v4, v10, v10
	v_and_b32_e32 v5, 0xffff0000, v5
	v_fmac_f32_e32 v4, v5, v5
	v_lshlrev_b32_e32 v5, 16, v6
	v_and_b32_e32 v6, 0xffff0000, v6
	v_mul_f32_e32 v6, v6, v6
	v_fmac_f32_e32 v6, v5, v5
	v_lshlrev_b32_e32 v5, 16, v7
	v_fmac_f32_e32 v6, v5, v5
	v_and_b32_e32 v5, 0xffff0000, v7
	v_fmac_f32_e32 v6, v5, v5
	v_add_f32_e32 v5, v9, v6
	v_lshlrev_b32_e32 v6, 16, v0
	v_and_b32_e32 v0, 0xffff0000, v0
	v_mul_f32_e32 v0, v0, v0
	v_fmac_f32_e32 v0, v6, v6
	v_lshlrev_b32_e32 v6, 16, v1
	v_add_f32_e32 v8, v28, v8
	v_fmac_f32_e32 v0, v6, v6
	v_and_b32_e32 v1, 0xffff0000, v1
	v_add_f32_e32 v4, v8, v4
	v_fmac_f32_e32 v0, v1, v1
	v_and_b32_e32 v1, 0xffff0000, v2
	v_add_f32_e32 v21, v4, v0
	v_lshlrev_b32_e32 v0, 16, v2
	v_mul_f32_e32 v1, v1, v1
	v_fmac_f32_e32 v1, v0, v0
	v_lshlrev_b32_e32 v0, 16, v3
	v_fmac_f32_e32 v1, v0, v0
	v_and_b32_e32 v0, 0xffff0000, v3
	v_fmac_f32_e32 v1, v0, v0
	v_add_f32_e32 v28, v5, v1
	global_load_dwordx4 v[0:3], v[14:15], off offset:112 nt
	global_load_dwordx4 v[4:7], v[14:15], off offset:96 nt
	global_load_dwordx4 v[8:11], v[14:15], off offset:80 nt
	global_load_dwordx4 v[30:33], v[14:15], off offset:64 nt
	s_waitcnt vmcnt(0)
	v_and_b32_e32 v15, 0xffff0000, v30
	v_lshlrev_b32_e32 v14, 16, v30
	v_mul_f32_e32 v15, v15, v15
	v_fmac_f32_e32 v15, v14, v14
	v_lshlrev_b32_e32 v14, 16, v31
	v_fmac_f32_e32 v15, v14, v14
	v_and_b32_e32 v14, 0xffff0000, v31
	v_fmac_f32_e32 v15, v14, v14
	v_add_f32_e32 v14, v21, v15
	v_and_b32_e32 v21, 0xffff0000, v32
	v_lshlrev_b32_e32 v15, 16, v32
	v_mul_f32_e32 v21, v21, v21
	v_fmac_f32_e32 v21, v15, v15
	v_lshlrev_b32_e32 v15, 16, v33
	v_fmac_f32_e32 v21, v15, v15
	v_and_b32_e32 v15, 0xffff0000, v33
	v_fmac_f32_e32 v21, v15, v15
	v_add_f32_e32 v15, v28, v21
	v_lshlrev_b32_e32 v21, 16, v8
	v_and_b32_e32 v8, 0xffff0000, v8
	v_mul_f32_e32 v8, v8, v8
	v_fmac_f32_e32 v8, v21, v21
	v_lshlrev_b32_e32 v21, 16, v9
	v_fmac_f32_e32 v8, v21, v21
	v_and_b32_e32 v9, 0xffff0000, v9
	v_fmac_f32_e32 v8, v9, v9
	v_lshlrev_b32_e32 v9, 16, v10
	v_and_b32_e32 v10, 0xffff0000, v10
	v_mul_f32_e32 v10, v10, v10
	v_fmac_f32_e32 v10, v9, v9
	v_lshlrev_b32_e32 v9, 16, v11
	v_fmac_f32_e32 v10, v9, v9
	v_and_b32_e32 v9, 0xffff0000, v11
	v_fmac_f32_e32 v10, v9, v9
	v_add_f32_e32 v9, v15, v10
	v_lshlrev_b32_e32 v10, 16, v4
	v_and_b32_e32 v4, 0xffff0000, v4
	v_mul_f32_e32 v4, v4, v4
	v_fmac_f32_e32 v4, v10, v10
	v_lshlrev_b32_e32 v10, 16, v5
	v_fmac_f32_e32 v4, v10, v10
	v_and_b32_e32 v5, 0xffff0000, v5
	v_fmac_f32_e32 v4, v5, v5
	v_lshlrev_b32_e32 v5, 16, v6
	v_and_b32_e32 v6, 0xffff0000, v6
	v_mul_f32_e32 v6, v6, v6
	v_fmac_f32_e32 v6, v5, v5
	v_lshlrev_b32_e32 v5, 16, v7
	v_fmac_f32_e32 v6, v5, v5
	v_and_b32_e32 v5, 0xffff0000, v7
	v_fmac_f32_e32 v6, v5, v5
	v_add_f32_e32 v5, v9, v6
	v_lshlrev_b32_e32 v6, 16, v0
	v_and_b32_e32 v0, 0xffff0000, v0
	v_mul_f32_e32 v0, v0, v0
	v_fmac_f32_e32 v0, v6, v6
	v_lshlrev_b32_e32 v6, 16, v1
	v_fmac_f32_e32 v0, v6, v6
	v_and_b32_e32 v1, 0xffff0000, v1
	v_fmac_f32_e32 v0, v1, v1
	v_lshlrev_b32_e32 v1, 16, v2
	v_and_b32_e32 v2, 0xffff0000, v2
	v_mul_f32_e32 v2, v2, v2
	v_fmac_f32_e32 v2, v1, v1
	v_lshlrev_b32_e32 v1, 16, v3
	v_add_f32_e32 v8, v14, v8
	v_fmac_f32_e32 v2, v1, v1
	v_and_b32_e32 v1, 0xffff0000, v3
	v_add_f32_e32 v4, v8, v4
	v_fmac_f32_e32 v2, v1, v1
	v_add_f32_e32 v0, v4, v0
	v_add_f32_e32 v1, v5, v2
	v_add_f32_e32 v0, v0, v1
	v_fmamk_f32 v21, v0, 0x3f800347, v217
	global_load_dwordx4 v[0:3], v[12:13], off offset:48 nt
	global_load_dwordx4 v[4:7], v[12:13], off offset:32 nt
	global_load_dwordx4 v[8:11], v[12:13], off offset:16 nt
	global_load_dwordx4 v[28:31], v[12:13], off nt
	s_waitcnt vmcnt(0)
; __device__ __forceinline__ float bf_lo(unsigned w) { return __uint_as_float(w << 16); }
; __device__ __forceinline__ float bf_hi(unsigned w) { return __uint_as_float(w & 0xffff0000u); }
; __device__ __forceinline__ void norm_unit(const Ctx& c, int l, int tile) {
;     ...
;         for (int hh = 0; hh < 2; ++hh) { const u32x4* p = (const u32x4*)((a == 0 ? Q : K) + (size_t)tok * 512 + (2 * part + hh) * 64);
;             float s0 = 0.f, s1 = 0.f;
; #pragma unroll
;             for (int j = 0; j < 8; ++j) { const u32x4 w = p[j];
;                 s0 += bf_lo(w.x) * bf_lo(w.x) + bf_hi(w.x) * bf_hi(w.x) + bf_lo(w.y) * bf_lo(w.y) + bf_hi(w.y) * bf_hi(w.y);
;                 s1 += bf_lo(w.z) * bf_lo(w.z) + bf_hi(w.z) * bf_hi(w.z) + bf_lo(w.w) * bf_lo(w.w) + bf_hi(w.w) * bf_hi(w.w); }
;             res[a * 2 + hh] = (s0 + s1) * 1.0001f + 1e-30f; }
; #pragma unroll
;     for (int i = 0; i < 4; ++i) { float v = res[i];
; #pragma unroll
;         for (int o = 4; o < 64; o <<= 1) v = fmaxf(v, __shfl_xor(v, o));
;         res[i] = v; }
;     if (c.lane < 4) {
; #pragma unroll
;         for (int a = 0; a < 2; ++a)
; #pragma unroll
;             for (int hh = 0; hh < 2; ++hh) atomicMax(nrm + (size_t)(b * 8 + 2 * part + hh) * 2 + a, __float_as_uint(res[a * 2 + hh]));
;     }
	v_and_b32_e32 v15, 0xffff0000, v28
	v_lshlrev_b32_e32 v14, 16, v28
	v_mul_f32_e32 v15, v15, v15
	v_fmac_f32_e32 v15, v14, v14
	v_lshlrev_b32_e32 v14, 16, v29
	v_fmac_f32_e32 v15, v14, v14
	v_and_b32_e32 v14, 0xffff0000, v29
	v_and_b32_e32 v19, 0xffff0000, v30
	v_fmac_f32_e32 v15, v14, v14
	v_lshlrev_b32_e32 v14, 16, v30
	v_mul_f32_e32 v19, v19, v19
	v_fmac_f32_e32 v19, v14, v14
	v_lshlrev_b32_e32 v14, 16, v31
	v_fmac_f32_e32 v19, v14, v14
	v_and_b32_e32 v14, 0xffff0000, v31
	v_fmac_f32_e32 v19, v14, v14
	v_lshlrev_b32_e32 v14, 16, v8
	v_and_b32_e32 v8, 0xffff0000, v8
	v_mul_f32_e32 v8, v8, v8
	v_fmac_f32_e32 v8, v14, v14
	v_lshlrev_b32_e32 v14, 16, v9
	v_fmac_f32_e32 v8, v14, v14
	v_and_b32_e32 v9, 0xffff0000, v9
	v_fmac_f32_e32 v8, v9, v9
	v_lshlrev_b32_e32 v9, 16, v10
	v_and_b32_e32 v10, 0xffff0000, v10
	v_mul_f32_e32 v10, v10, v10
	v_fmac_f32_e32 v10, v9, v9
	v_lshlrev_b32_e32 v9, 16, v11
	v_fmac_f32_e32 v10, v9, v9
	v_and_b32_e32 v9, 0xffff0000, v11
	v_fmac_f32_e32 v10, v9, v9
	v_add_f32_e32 v9, v19, v10
	v_lshlrev_b32_e32 v10, 16, v4
	v_and_b32_e32 v4, 0xffff0000, v4
	v_mul_f32_e32 v4, v4, v4
	v_fmac_f32_e32 v4, v10, v10
	v_lshlrev_b32_e32 v10, 16, v5
	v_fmac_f32_e32 v4, v10, v10
	v_and_b32_e32 v5, 0xffff0000, v5
	v_fmac_f32_e32 v4, v5, v5
	v_lshlrev_b32_e32 v5, 16, v6
	v_and_b32_e32 v6, 0xffff0000, v6
	v_mul_f32_e32 v6, v6, v6
	v_fmac_f32_e32 v6, v5, v5
	v_lshlrev_b32_e32 v5, 16, v7
	v_fmac_f32_e32 v6, v5, v5
	v_and_b32_e32 v5, 0xffff0000, v7
	v_fmac_f32_e32 v6, v5, v5
	v_add_f32_e32 v5, v9, v6
	v_lshlrev_b32_e32 v6, 16, v0
	v_and_b32_e32 v0, 0xffff0000, v0
	v_mul_f32_e32 v0, v0, v0
	v_fmac_f32_e32 v0, v6, v6
	v_lshlrev_b32_e32 v6, 16, v1
	v_add_f32_e32 v8, v15, v8
	v_fmac_f32_e32 v0, v6, v6
	v_and_b32_e32 v1, 0xffff0000, v1
	v_add_f32_e32 v4, v8, v4
	v_fmac_f32_e32 v0, v1, v1
	v_and_b32_e32 v1, 0xffff0000, v2
	v_add_f32_e32 v28, v4, v0
	v_lshlrev_b32_e32 v0, 16, v2
	v_mul_f32_e32 v1, v1, v1
	v_fmac_f32_e32 v1, v0, v0
	v_lshlrev_b32_e32 v0, 16, v3
	v_fmac_f32_e32 v1, v0, v0
	v_and_b32_e32 v0, 0xffff0000, v3
	v_fmac_f32_e32 v1, v0, v0
	v_add_f32_e32 v19, v5, v1
	global_load_dwordx4 v[0:3], v[12:13], off offset:112 nt
	global_load_dwordx4 v[4:7], v[12:13], off offset:96 nt
	global_load_dwordx4 v[8:11], v[12:13], off offset:80 nt
	s_nop 0
	global_load_dwordx4 v[12:15], v[12:13], off offset:64 nt
	s_waitcnt vmcnt(0)
	v_lshlrev_b32_e32 v29, 16, v12
	v_and_b32_e32 v12, 0xffff0000, v12
	v_mul_f32_e32 v12, v12, v12
	v_fmac_f32_e32 v12, v29, v29
	v_lshlrev_b32_e32 v29, 16, v13
	v_fmac_f32_e32 v12, v29, v29
	v_and_b32_e32 v13, 0xffff0000, v13
	v_fmac_f32_e32 v12, v13, v13
	v_lshlrev_b32_e32 v13, 16, v14
	v_and_b32_e32 v14, 0xffff0000, v14
	v_mul_f32_e32 v14, v14, v14
	v_fmac_f32_e32 v14, v13, v13
	v_lshlrev_b32_e32 v13, 16, v15
	v_fmac_f32_e32 v14, v13, v13
	v_and_b32_e32 v13, 0xffff0000, v15
	v_fmac_f32_e32 v14, v13, v13
	v_add_f32_e32 v13, v19, v14
	v_lshlrev_b32_e32 v14, 16, v8
	v_and_b32_e32 v8, 0xffff0000, v8
	v_mul_f32_e32 v8, v8, v8
	v_fmac_f32_e32 v8, v14, v14
	v_lshlrev_b32_e32 v14, 16, v9
	v_fmac_f32_e32 v8, v14, v14
	v_and_b32_e32 v9, 0xffff0000, v9
	v_fmac_f32_e32 v8, v9, v9
	v_lshlrev_b32_e32 v9, 16, v10
	v_and_b32_e32 v10, 0xffff0000, v10
	v_mul_f32_e32 v10, v10, v10
	v_fmac_f32_e32 v10, v9, v9
	v_lshlrev_b32_e32 v9, 16, v11
	v_fmac_f32_e32 v10, v9, v9
	v_and_b32_e32 v9, 0xffff0000, v11
	v_fmac_f32_e32 v10, v9, v9
	v_add_f32_e32 v9, v13, v10
	v_lshlrev_b32_e32 v10, 16, v4
	v_and_b32_e32 v4, 0xffff0000, v4
	v_mul_f32_e32 v4, v4, v4
	v_fmac_f32_e32 v4, v10, v10
	v_lshlrev_b32_e32 v10, 16, v5
	v_fmac_f32_e32 v4, v10, v10
	v_and_b32_e32 v5, 0xffff0000, v5
	v_fmac_f32_e32 v4, v5, v5
	v_lshlrev_b32_e32 v5, 16, v6
	v_and_b32_e32 v6, 0xffff0000, v6
	v_mul_f32_e32 v6, v6, v6
	v_fmac_f32_e32 v6, v5, v5
	v_lshlrev_b32_e32 v5, 16, v7
	v_fmac_f32_e32 v6, v5, v5
	v_and_b32_e32 v5, 0xffff0000, v7
	v_fmac_f32_e32 v6, v5, v5
	v_add_f32_e32 v5, v9, v6
	v_lshlrev_b32_e32 v6, 16, v0
	v_and_b32_e32 v0, 0xffff0000, v0
	v_mul_f32_e32 v0, v0, v0
	v_fmac_f32_e32 v0, v6, v6
	v_lshlrev_b32_e32 v6, 16, v1
	v_fmac_f32_e32 v0, v6, v6
	v_and_b32_e32 v1, 0xffff0000, v1
	v_fmac_f32_e32 v0, v1, v1
	v_lshlrev_b32_e32 v1, 16, v2
	v_and_b32_e32 v2, 0xffff0000, v2
	v_mul_f32_e32 v2, v2, v2
	v_add_f32_e32 v12, v28, v12
	v_fmac_f32_e32 v2, v1, v1
	v_lshlrev_b32_e32 v1, 16, v3
	v_add_f32_e32 v8, v12, v8
	v_fmac_f32_e32 v2, v1, v1
	v_and_b32_e32 v1, 0xffff0000, v3
	v_add_f32_e32 v4, v8, v4
	v_fmac_f32_e32 v2, v1, v1
	v_add_f32_e32 v0, v4, v0
	v_add_f32_e32 v1, v5, v2
	v_add_f32_e32 v0, v0, v1
	v_fmamk_f32 v6, v0, 0x3f800347, v217
	ds_bpermute_b32 v0, v22, v17
	ds_bpermute_b32 v2, v22, v20
	ds_bpermute_b32 v4, v22, v21
	ds_bpermute_b32 v7, v22, v6
	s_waitcnt lgkmcnt(3)
	v_max_f32_e32 v0, v0, v0
	s_waitcnt lgkmcnt(2)
	v_max_f32_e32 v2, v2, v2
	s_waitcnt lgkmcnt(1)
	v_max_f32_e32 v4, v4, v4
	s_waitcnt lgkmcnt(0)
	v_max_f32_e32 v7, v7, v7
	v_max_f32_e32 v0, v17, v0
	v_max_f32_e32 v2, v20, v2
	v_max_f32_e32 v4, v21, v4
	v_max_f32_e32 v6, v6, v7
	ds_bpermute_b32 v1, v23, v0
	ds_bpermute_b32 v3, v23, v2
	ds_bpermute_b32 v5, v23, v4
	ds_bpermute_b32 v7, v23, v6
	s_waitcnt lgkmcnt(3)
	v_max_f32_e32 v1, v1, v1
	s_waitcnt lgkmcnt(2)
	v_max_f32_e32 v3, v3, v3
	s_waitcnt lgkmcnt(1)
	v_max_f32_e32 v5, v5, v5
	s_waitcnt lgkmcnt(0)
	v_max_f32_e32 v7, v7, v7
	v_max_f32_e32 v0, v0, v1
	v_max_f32_e32 v2, v2, v3
	v_max_f32_e32 v4, v4, v5
	v_max_f32_e32 v6, v6, v7
	ds_bpermute_b32 v1, v24, v0
	ds_bpermute_b32 v3, v24, v2
	ds_bpermute_b32 v5, v24, v4
	ds_bpermute_b32 v7, v24, v6
	s_waitcnt lgkmcnt(3)
	v_max_f32_e32 v1, v1, v1
	s_waitcnt lgkmcnt(2)
	v_max_f32_e32 v3, v3, v3
	s_waitcnt lgkmcnt(1)
	v_max_f32_e32 v5, v5, v5
	s_waitcnt lgkmcnt(0)
	v_max_f32_e32 v7, v7, v7
	v_max_f32_e32 v0, v0, v1
	v_max_f32_e32 v2, v2, v3
	v_max_f32_e32 v4, v4, v5
	v_max_f32_e32 v6, v6, v7
	ds_bpermute_b32 v1, v25, v0
	ds_bpermute_b32 v3, v25, v2
	ds_bpermute_b32 v5, v25, v4
	ds_bpermute_b32 v7, v25, v6
	s_and_saveexec_b64 s[42:43], s[38:39]
	s_cbranch_execz .LBB0_313
	s_waitcnt lgkmcnt(0)
	v_max_f32_e32 v7, v7, v7
	v_max_f32_e32 v6, v6, v6
	v_max_f32_e32 v1, v1, v1
	v_max_f32_e32 v0, v0, v0
	v_max_f32_e32 v6, v6, v7
	v_max_f32_e32 v7, v0, v1
	v_max_f32_e32 v0, v3, v3
	v_max_f32_e32 v1, v2, v2
	v_max_f32_e32 v8, v1, v0
	v_max_f32_e32 v0, v5, v5
	v_max_f32_e32 v1, v4, v4
	s_ashr_i32 s6, s0, 2
	v_max_f32_e32 v4, v1, v0
	v_and_or_b32 v0, s6, -8, v27
	v_ashrrev_i32_e32 v1, 31, v0
	v_lshl_add_u64 v[2:3], v[0:1], 3, s[40:41]
	v_or_b32_e32 v0, 1, v0
	v_ashrrev_i32_e32 v1, 31, v0
	global_atomic_umax v[2:3], v7, off
	v_lshl_add_u64 v[0:1], v[0:1], 3, s[40:41]
	global_atomic_umax v[0:1], v8, off
	global_atomic_umax v[2:3], v4, off offset:4
	global_atomic_umax v[0:1], v6, off offset:4
	s_branch .LBB0_313
